# gla_scan: 4 decay-staging loads issued together into fresh regs, ds_writes+barrier moved after the 64 dST loads (overlap staging latency with dST load latency)
# speedup vs baseline: 1.0049x; 1.0010x over previous
; #define LAS __attribute__((address_space(3)))
; DI void gla_scan(const Params& p, int G, LAS unsigned char* lds) {
;     ...
;     for (int e0 = blockIdx.x * 512; e0 < 16 * 8192; e0 += G * 512) {
;         const int e = e0 + tid, bh = e0 >> 13, vk = e & 8191, k = e & 63, b = bh >> 2, h = bh & 3;
;         __syncthreads();
; #pragma unroll
;         for (int i4 = 0; i4 < 4; ++i4) { const int idx = tid * 4 + 2048 * i4, n = idx >> 6, kk = idx & 63;
;             *(LAS f32x4*)(dl + idx) = *(const f32x4*)(decay + (size_t)(b * 128 + n) * 256 + h * 64 + kk); }
;         __syncthreads();
;         const float* dp = dST + (size_t)bh * 128 * 8192 + vk; bf16_t* sp = SpT + (size_t)bh * 128 * 8192 + vk;
;         float st = 0.f;
;         for (int n0 = 0; n0 < 128; n0 += 64) { float dv[64];
; #pragma unroll
;             for (int j2 = 0; j2 < 64; ++j2) dv[j2] = __builtin_nontemporal_load(dp + (size_t)(n0 + j2) * 8192);
.LBB0_434:
	s_ashr_i32 s9, s80, 8
	s_ashr_i32 s8, s80, 13
	s_and_b32 s9, s9, 0xffffff80
	s_lshl_b32 s20, s8, 8
	v_add_u32_e32 v4, s9, v12
	s_and_b32 s30, s20, 0x300
	v_ashrrev_i32_e32 v5, 31, v4
	v_lshl_add_u64 v[8:9], v[2:3], 0, s[30:31]
	v_lshlrev_b64 v[4:5], 10, v[4:5]
	v_lshl_add_u64 v[4:5], v[8:9], 0, v[4:5]
	s_waitcnt vmcnt(0)
	s_barrier
	global_load_dwordx4 v[100:103], v[4:5], off
	v_add_u32_e32 v0, s80, v10
	v_add_u32_e32 v4, s9, v14
	v_ashrrev_i32_e32 v5, 31, v4
	v_lshlrev_b64 v[4:5], 10, v[4:5]
	v_lshl_add_u64 v[4:5], v[8:9], 0, v[4:5]
	global_load_dwordx4 v[104:107], v[4:5], off
	v_add_u32_e32 v4, s9, v15
	v_ashrrev_i32_e32 v5, 31, v4
	v_lshlrev_b64 v[4:5], 10, v[4:5]
	v_lshl_add_u64 v[4:5], v[8:9], 0, v[4:5]
	global_load_dwordx4 v[108:111], v[4:5], off
	v_add_u32_e32 v4, s9, v16
	v_ashrrev_i32_e32 v5, 31, v4
	v_lshlrev_b64 v[4:5], 10, v[4:5]
	v_lshl_add_u64 v[4:5], v[8:9], 0, v[4:5]
	global_load_dwordx4 v[112:115], v[4:5], off
	s_ashr_i32 s9, s8, 31
	s_lshl_b64 s[20:21], s[8:9], 22
	s_add_u32 s22, s96, s20
	s_addc_u32 s23, s97, s21
	s_lshl_b64 s[8:9], s[8:9], 21
	s_add_u32 s20, s94, s8
	s_addc_u32 s21, s95, s9
	v_mov_b32_e32 v9, v1
	s_mov_b32 s8, 0x1f8000
	s_add_i32 s80, s80, s34
	s_cmp_lt_i32 s80, 0x20000
	v_and_b32_e32 v4, 0x1fff, v0
	v_lshlrev_b32_e32 v0, 2, v4
	v_lshl_add_u64 v[6:7], s[22:23], 0, v[0:1]
	v_add_co_u32_e32 v18, vcc, s38, v6
	s_nop 1
	v_addc_co_u32_e32 v19, vcc, 0, v7, vcc
	global_load_dword v78, v0, s[22:23] nt
	global_load_dword v77, v[18:19], off nt
	v_add_co_u32_e32 v18, vcc, s39, v6
	v_lshlrev_b32_e32 v8, 1, v4
	s_nop 0
	v_addc_co_u32_e32 v19, vcc, 0, v7, vcc
	global_load_dword v76, v[18:19], off nt
	v_add_co_u32_e32 v18, vcc, s40, v6
	v_lshl_add_u64 v[4:5], s[20:21], 0, v[8:9]
	s_nop 0
	v_addc_co_u32_e32 v19, vcc, 0, v7, vcc
	global_load_dword v75, v[18:19], off nt
	v_add_co_u32_e32 v18, vcc, s41, v6
	global_store_short v8, v1, s[20:21]
	s_nop 0
	v_addc_co_u32_e32 v19, vcc, 0, v7, vcc
	global_load_dword v74, v[18:19], off nt
	v_add_co_u32_e32 v18, vcc, s42, v6
	s_nop 1
	v_addc_co_u32_e32 v19, vcc, 0, v7, vcc
	global_load_dword v73, v[18:19], off nt
	v_add_co_u32_e32 v18, vcc, s43, v6
	s_nop 1
	v_addc_co_u32_e32 v19, vcc, 0, v7, vcc
	global_load_dword v72, v[18:19], off nt
	v_add_co_u32_e32 v18, vcc, s44, v6
	s_nop 1
	v_addc_co_u32_e32 v19, vcc, 0, v7, vcc
	global_load_dword v71, v[18:19], off nt
	v_add_co_u32_e32 v18, vcc, s45, v6
	s_nop 1
	v_addc_co_u32_e32 v19, vcc, 0, v7, vcc
	global_load_dword v70, v[18:19], off nt
	v_add_co_u32_e32 v18, vcc, s46, v6
	s_nop 1
	v_addc_co_u32_e32 v19, vcc, 0, v7, vcc
	global_load_dword v69, v[18:19], off nt
	v_add_co_u32_e32 v18, vcc, s47, v6
	s_nop 1
	v_addc_co_u32_e32 v19, vcc, 0, v7, vcc
	global_load_dword v68, v[18:19], off nt
	v_add_co_u32_e32 v18, vcc, s48, v6
	s_nop 1
	v_addc_co_u32_e32 v19, vcc, 0, v7, vcc
	global_load_dword v67, v[18:19], off nt
	v_add_co_u32_e32 v18, vcc, s49, v6
	s_nop 1
	v_addc_co_u32_e32 v19, vcc, 0, v7, vcc
	global_load_dword v66, v[18:19], off nt
	v_add_co_u32_e32 v18, vcc, s50, v6
	s_nop 1
	v_addc_co_u32_e32 v19, vcc, 0, v7, vcc
	global_load_dword v65, v[18:19], off nt
	v_add_co_u32_e32 v18, vcc, s51, v6
	s_nop 1
	v_addc_co_u32_e32 v19, vcc, 0, v7, vcc
	global_load_dword v64, v[18:19], off nt
	v_add_co_u32_e32 v18, vcc, s52, v6
	s_nop 1
	v_addc_co_u32_e32 v19, vcc, 0, v7, vcc
	global_load_dword v63, v[18:19], off nt
	v_add_co_u32_e32 v18, vcc, s53, v6
	s_nop 1
	v_addc_co_u32_e32 v19, vcc, 0, v7, vcc
	global_load_dword v62, v[18:19], off nt
	v_add_co_u32_e32 v18, vcc, s55, v6
	s_nop 1
	v_addc_co_u32_e32 v19, vcc, 0, v7, vcc
	global_load_dword v61, v[18:19], off nt
	v_add_co_u32_e32 v18, vcc, s56, v6
	s_nop 1
	v_addc_co_u32_e32 v19, vcc, 0, v7, vcc
	global_load_dword v60, v[18:19], off nt
	v_add_co_u32_e32 v18, vcc, s57, v6
	s_nop 1
	v_addc_co_u32_e32 v19, vcc, 0, v7, vcc
	global_load_dword v59, v[18:19], off nt
	v_add_co_u32_e32 v18, vcc, s58, v6
	s_nop 1
	v_addc_co_u32_e32 v19, vcc, 0, v7, vcc
	global_load_dword v58, v[18:19], off nt
	v_add_co_u32_e32 v18, vcc, s59, v6
	s_nop 1
	v_addc_co_u32_e32 v19, vcc, 0, v7, vcc
	global_load_dword v57, v[18:19], off nt
	v_add_co_u32_e32 v18, vcc, s60, v6
	s_nop 1
	v_addc_co_u32_e32 v19, vcc, 0, v7, vcc
	global_load_dword v56, v[18:19], off nt
	v_add_co_u32_e32 v18, vcc, s61, v6
	s_nop 1
	v_addc_co_u32_e32 v19, vcc, 0, v7, vcc
	global_load_dword v55, v[18:19], off nt
	v_add_co_u32_e32 v18, vcc, s62, v6
	s_nop 1
	v_addc_co_u32_e32 v19, vcc, 0, v7, vcc
	global_load_dword v54, v[18:19], off nt
	v_add_co_u32_e32 v18, vcc, s63, v6
	s_nop 1
	v_addc_co_u32_e32 v19, vcc, 0, v7, vcc
	global_load_dword v53, v[18:19], off nt
	v_add_co_u32_e32 v18, vcc, s64, v6
	s_nop 1
	v_addc_co_u32_e32 v19, vcc, 0, v7, vcc
	global_load_dword v52, v[18:19], off nt
	v_add_co_u32_e32 v18, vcc, s65, v6
	s_nop 1
	v_addc_co_u32_e32 v19, vcc, 0, v7, vcc
	global_load_dword v51, v[18:19], off nt
	v_add_co_u32_e32 v18, vcc, s66, v6
	s_nop 1
	v_addc_co_u32_e32 v19, vcc, 0, v7, vcc
	global_load_dword v50, v[18:19], off nt
	v_add_co_u32_e32 v18, vcc, s67, v6
	s_nop 1
	v_addc_co_u32_e32 v19, vcc, 0, v7, vcc
	global_load_dword v49, v[18:19], off nt
	v_add_co_u32_e32 v18, vcc, s68, v6
	s_nop 1
	v_addc_co_u32_e32 v19, vcc, 0, v7, vcc
	global_load_dword v48, v[18:19], off nt
	v_add_co_u32_e32 v18, vcc, s69, v6
	s_nop 1
	v_addc_co_u32_e32 v19, vcc, 0, v7, vcc
	global_load_dword v47, v[18:19], off nt
	v_add_co_u32_e32 v18, vcc, s70, v6
	s_nop 1
	v_addc_co_u32_e32 v19, vcc, 0, v7, vcc
	global_load_dword v46, v[18:19], off nt
	v_add_co_u32_e32 v18, vcc, s71, v6
	s_nop 1
	v_addc_co_u32_e32 v19, vcc, 0, v7, vcc
	global_load_dword v45, v[18:19], off nt
; #define LAS __attribute__((address_space(3)))
; DI bf16_t f2bf(float f) { return (bf16_t)(pk2(f, 0.f) & 0xffffu); }
; DI void gla_scan(const Params& p, int G, LAS unsigned char* lds) {
;     ...
;         for (int i4 = 0; i4 < 4; ++i4) { const int idx = tid * 4 + 2048 * i4, n = idx >> 6, kk = idx & 63;
;             *(LAS f32x4*)(dl + idx) = *(const f32x4*)(decay + (size_t)(b * 128 + n) * 256 + h * 64 + kk); }
;         __syncthreads();
;         const float* dp = dST + (size_t)bh * 128 * 8192 + vk; bf16_t* sp = SpT + (size_t)bh * 128 * 8192 + vk;
;         float st = 0.f;
;         for (int n0 = 0; n0 < 128; n0 += 64) { float dv[64];
; #pragma unroll
;             for (int j2 = 0; j2 < 64; ++j2) dv[j2] = __builtin_nontemporal_load(dp + (size_t)(n0 + j2) * 8192);
; #pragma unroll
;             for (int j2 = 0; j2 < 64; ++j2) { sp[(size_t)(n0 + j2) * 8192] = f2bf(st); st = dl[(n0 + j2) * 64 + k] * st + dv[j2]; } }
	v_add_co_u32_e32 v18, vcc, s72, v6
	s_nop 1
	v_addc_co_u32_e32 v19, vcc, 0, v7, vcc
	global_load_dword v44, v[18:19], off nt
	v_add_co_u32_e32 v18, vcc, s73, v6
	s_nop 1
	v_addc_co_u32_e32 v19, vcc, 0, v7, vcc
	global_load_dword v43, v[18:19], off nt
	v_add_co_u32_e32 v18, vcc, s78, v6
	s_nop 1
	v_addc_co_u32_e32 v19, vcc, 0, v7, vcc
	global_load_dword v42, v[18:19], off nt
	v_add_co_u32_e32 v18, vcc, s79, v6
	s_nop 1
	v_addc_co_u32_e32 v19, vcc, 0, v7, vcc
	global_load_dword v41, v[18:19], off nt
	v_add_co_u32_e32 v18, vcc, s81, v6
	s_nop 1
	v_addc_co_u32_e32 v19, vcc, 0, v7, vcc
	global_load_dword v40, v[18:19], off nt
	v_add_co_u32_e32 v18, vcc, s83, v6
	s_nop 1
	v_addc_co_u32_e32 v19, vcc, 0, v7, vcc
	global_load_dword v39, v[18:19], off nt
	v_add_co_u32_e32 v18, vcc, s84, v6
	s_nop 1
	v_addc_co_u32_e32 v19, vcc, 0, v7, vcc
	global_load_dword v38, v[18:19], off nt
	v_add_co_u32_e32 v18, vcc, s85, v6
	s_nop 1
	v_addc_co_u32_e32 v19, vcc, 0, v7, vcc
	global_load_dword v37, v[18:19], off nt
	v_add_co_u32_e32 v18, vcc, s87, v6
	s_nop 1
	v_addc_co_u32_e32 v19, vcc, 0, v7, vcc
	global_load_dword v36, v[18:19], off nt
	v_add_co_u32_e32 v18, vcc, s88, v6
	s_nop 1
	v_addc_co_u32_e32 v19, vcc, 0, v7, vcc
	global_load_dword v35, v[18:19], off nt
	v_add_co_u32_e32 v18, vcc, s89, v6
	s_nop 1
	v_addc_co_u32_e32 v19, vcc, 0, v7, vcc
	global_load_dword v34, v[18:19], off nt
	v_add_co_u32_e32 v18, vcc, s35, v6
	s_nop 1
	v_addc_co_u32_e32 v19, vcc, 0, v7, vcc
	global_load_dword v33, v[18:19], off nt
	v_add_co_u32_e32 v18, vcc, s86, v6
	s_nop 1
	v_addc_co_u32_e32 v19, vcc, 0, v7, vcc
	global_load_dword v32, v[18:19], off nt
	v_add_co_u32_e32 v18, vcc, s90, v6
	s_nop 1
	v_addc_co_u32_e32 v19, vcc, 0, v7, vcc
	global_load_dword v31, v[18:19], off nt
	v_add_co_u32_e32 v18, vcc, s91, v6
	s_nop 1
	v_addc_co_u32_e32 v19, vcc, 0, v7, vcc
	global_load_dword v30, v[18:19], off nt
	v_add_co_u32_e32 v18, vcc, s18, v6
	s_nop 1
	v_addc_co_u32_e32 v19, vcc, 0, v7, vcc
	global_load_dword v29, v[18:19], off nt
	v_add_co_u32_e32 v18, vcc, s19, v6
	s_nop 1
	v_addc_co_u32_e32 v19, vcc, 0, v7, vcc
	global_load_dword v28, v[18:19], off nt
	v_add_co_u32_e32 v18, vcc, s36, v6
	s_nop 1
	v_addc_co_u32_e32 v19, vcc, 0, v7, vcc
	global_load_dword v27, v[18:19], off nt
	v_add_co_u32_e32 v18, vcc, s37, v6
	s_nop 1
	v_addc_co_u32_e32 v19, vcc, 0, v7, vcc
	global_load_dword v26, v[18:19], off nt
	v_add_co_u32_e32 v18, vcc, s6, v6
	s_nop 1
	v_addc_co_u32_e32 v19, vcc, 0, v7, vcc
	global_load_dword v25, v[18:19], off nt
	v_add_co_u32_e32 v18, vcc, s7, v6
	s_nop 1
	v_addc_co_u32_e32 v19, vcc, 0, v7, vcc
	global_load_dword v24, v[18:19], off nt
	v_add_co_u32_e32 v18, vcc, s0, v6
	s_nop 1
	v_addc_co_u32_e32 v19, vcc, 0, v7, vcc
	global_load_dword v23, v[18:19], off nt
	v_add_co_u32_e32 v18, vcc, s1, v6
	s_nop 1
	v_addc_co_u32_e32 v19, vcc, 0, v7, vcc
	global_load_dword v22, v[18:19], off nt
	v_add_co_u32_e32 v18, vcc, s4, v6
	s_nop 1
	v_addc_co_u32_e32 v19, vcc, 0, v7, vcc
	global_load_dword v21, v[18:19], off nt
	v_add_co_u32_e32 v18, vcc, s5, v6
	s_nop 1
	v_addc_co_u32_e32 v19, vcc, 0, v7, vcc
	global_load_dword v20, v[18:19], off nt
	v_add_co_u32_e32 v18, vcc, s92, v6
	s_nop 1
	v_addc_co_u32_e32 v19, vcc, 0, v7, vcc
	v_add_co_u32_e32 v80, vcc, s93, v6
	global_load_dword v18, v[18:19], off nt
	s_nop 0
	v_addc_co_u32_e32 v81, vcc, 0, v7, vcc
	global_load_dword v17, v[80:81], off nt
	v_add_co_u32_e32 v80, vcc, s12, v6
	s_nop 1
	v_addc_co_u32_e32 v81, vcc, 0, v7, vcc
	global_load_dword v9, v[80:81], off nt
	v_add_co_u32_e32 v80, vcc, s13, v6
	s_nop 1
	v_addc_co_u32_e32 v81, vcc, 0, v7, vcc
	global_load_dword v0, v[80:81], off nt
	v_add_co_u32_e32 v80, vcc, s8, v6
	s_movk_i32 s8, 0x4000
	s_nop 0
	v_addc_co_u32_e32 v81, vcc, 0, v7, vcc
	global_load_dword v19, v[80:81], off nt
	s_waitcnt vmcnt(63)
	ds_write_b128 v13, v[100:103]
	ds_write_b128 v13, v[104:107] offset:8192
	ds_write_b128 v13, v[108:111] offset:16384
	ds_write_b128 v13, v[112:115] offset:24576
	s_waitcnt lgkmcnt(0)
	s_barrier
	ds_read2st64_b32 v[80:81], v11 offset1:1
	v_add_co_u32_e32 v82, vcc, s8, v4
	s_mov_b32 s8, 0xc000
	s_nop 0
	v_addc_co_u32_e32 v83, vcc, 0, v5, vcc
	s_waitcnt vmcnt(62) lgkmcnt(0)
	v_fmac_f32_e32 v78, 0, v80
	v_cvt_pk_bf16_f32 v8, v78, s0
	v_fmac_f32_e32 v77, v78, v81
	v_add_co_u32_e32 v78, vcc, s38, v4
	global_store_short v[82:83], v8, off
	v_cvt_pk_bf16_f32 v8, v77, s0
	v_addc_co_u32_e32 v79, vcc, 0, v5, vcc
	global_store_short v[78:79], v8, off
	ds_read2st64_b32 v[78:79], v11 offset0:2 offset1:3
	v_add_co_u32_e32 v80, vcc, s8, v4
	s_mov_b32 s8, 0x14000
	s_nop 0
	v_addc_co_u32_e32 v81, vcc, 0, v5, vcc
	s_waitcnt lgkmcnt(0)
	v_fmac_f32_e32 v76, v77, v78
	v_cvt_pk_bf16_f32 v8, v76, s0
	s_waitcnt vmcnt(62)
	v_fmac_f32_e32 v75, v76, v79
	v_add_co_u32_e32 v76, vcc, s39, v4
	global_store_short v[80:81], v8, off
	v_cvt_pk_bf16_f32 v8, v75, s0
	v_addc_co_u32_e32 v77, vcc, 0, v5, vcc
	global_store_short v[76:77], v8, off
	ds_read2st64_b32 v[76:77], v11 offset0:4 offset1:5
	v_add_co_u32_e32 v78, vcc, s8, v4
	s_mov_b32 s8, 0x1c000
	s_nop 0
	v_addc_co_u32_e32 v79, vcc, 0, v5, vcc
	s_waitcnt vmcnt(62) lgkmcnt(0)
	v_fmac_f32_e32 v74, v75, v76
	v_cvt_pk_bf16_f32 v8, v74, s0
	v_fmac_f32_e32 v73, v74, v77
	v_add_co_u32_e32 v74, vcc, s40, v4
	global_store_short v[78:79], v8, off
	v_cvt_pk_bf16_f32 v8, v73, s0
	v_addc_co_u32_e32 v75, vcc, 0, v5, vcc
	global_store_short v[74:75], v8, off
	ds_read2st64_b32 v[74:75], v11 offset0:6 offset1:7
	v_add_co_u32_e32 v76, vcc, s8, v4
	s_mov_b32 s8, 0x24000
	s_nop 0
	v_addc_co_u32_e32 v77, vcc, 0, v5, vcc
	s_waitcnt vmcnt(62) lgkmcnt(0)
; DI bf16_t f2bf(float f) { return (bf16_t)(pk2(f, 0.f) & 0xffffu); }
; DI void gla_scan(const Params& p, int G, LAS unsigned char* lds) {
;     ...
; #pragma unroll
;             for (int j2 = 0; j2 < 64; ++j2) { sp[(size_t)(n0 + j2) * 8192] = f2bf(st); st = dl[(n0 + j2) * 64 + k] * st + dv[j2]; } }
	v_fmac_f32_e32 v72, v73, v74
	v_cvt_pk_bf16_f32 v8, v72, s0
	v_fmac_f32_e32 v71, v72, v75
	v_add_co_u32_e32 v72, vcc, s41, v4
	global_store_short v[76:77], v8, off
	v_cvt_pk_bf16_f32 v8, v71, s0
	v_addc_co_u32_e32 v73, vcc, 0, v5, vcc
	global_store_short v[72:73], v8, off
	ds_read2st64_b32 v[72:73], v11 offset0:8 offset1:9
	v_add_co_u32_e32 v74, vcc, s8, v4
	s_mov_b32 s8, 0x2c000
	s_nop 0
	v_addc_co_u32_e32 v75, vcc, 0, v5, vcc
	s_waitcnt vmcnt(62) lgkmcnt(0)
	v_fmac_f32_e32 v70, v71, v72
	v_cvt_pk_bf16_f32 v8, v70, s0
	v_fmac_f32_e32 v69, v70, v73
	v_add_co_u32_e32 v70, vcc, s42, v4
	global_store_short v[74:75], v8, off
	v_cvt_pk_bf16_f32 v8, v69, s0
	v_addc_co_u32_e32 v71, vcc, 0, v5, vcc
	global_store_short v[70:71], v8, off
	ds_read2st64_b32 v[70:71], v11 offset0:10 offset1:11
	v_add_co_u32_e32 v72, vcc, s8, v4
	s_mov_b32 s8, 0x34000
	s_nop 0
	v_addc_co_u32_e32 v73, vcc, 0, v5, vcc
	s_waitcnt vmcnt(62) lgkmcnt(0)
	v_fmac_f32_e32 v68, v69, v70
	v_cvt_pk_bf16_f32 v8, v68, s0
	v_fmac_f32_e32 v67, v68, v71
	v_add_co_u32_e32 v68, vcc, s43, v4
	global_store_short v[72:73], v8, off
	v_cvt_pk_bf16_f32 v8, v67, s0
	v_addc_co_u32_e32 v69, vcc, 0, v5, vcc
	global_store_short v[68:69], v8, off
	ds_read2st64_b32 v[68:69], v11 offset0:12 offset1:13
	v_add_co_u32_e32 v70, vcc, s8, v4
	s_mov_b32 s8, 0x3c000
	s_nop 0
	v_addc_co_u32_e32 v71, vcc, 0, v5, vcc
	s_waitcnt vmcnt(62) lgkmcnt(0)
	v_fmac_f32_e32 v66, v67, v68
	v_cvt_pk_bf16_f32 v8, v66, s0
	v_fmac_f32_e32 v65, v66, v69
	v_add_co_u32_e32 v66, vcc, s44, v4
	global_store_short v[70:71], v8, off
	v_cvt_pk_bf16_f32 v8, v65, s0
	v_addc_co_u32_e32 v67, vcc, 0, v5, vcc
	global_store_short v[66:67], v8, off
	ds_read2st64_b32 v[66:67], v11 offset0:14 offset1:15
	v_add_co_u32_e32 v68, vcc, s8, v4
	s_mov_b32 s8, 0x44000
	s_nop 0
	v_addc_co_u32_e32 v69, vcc, 0, v5, vcc
	s_waitcnt vmcnt(62) lgkmcnt(0)
	v_fmac_f32_e32 v64, v65, v66
	v_cvt_pk_bf16_f32 v8, v64, s0
	v_fmac_f32_e32 v63, v64, v67
	v_add_co_u32_e32 v64, vcc, s45, v4
	global_store_short v[68:69], v8, off
	v_cvt_pk_bf16_f32 v8, v63, s0
	v_addc_co_u32_e32 v65, vcc, 0, v5, vcc
	global_store_short v[64:65], v8, off
	ds_read2st64_b32 v[64:65], v11 offset0:16 offset1:17
	v_add_co_u32_e32 v66, vcc, s8, v4
	s_mov_b32 s8, 0x4c000
	s_nop 0
	v_addc_co_u32_e32 v67, vcc, 0, v5, vcc
	s_waitcnt vmcnt(62) lgkmcnt(0)
	v_fmac_f32_e32 v62, v63, v64
	v_cvt_pk_bf16_f32 v8, v62, s0
	v_fmac_f32_e32 v61, v62, v65
	v_add_co_u32_e32 v62, vcc, s46, v4
	global_store_short v[66:67], v8, off
	v_cvt_pk_bf16_f32 v8, v61, s0
	v_addc_co_u32_e32 v63, vcc, 0, v5, vcc
	global_store_short v[62:63], v8, off
	ds_read2st64_b32 v[62:63], v11 offset0:18 offset1:19
	v_add_co_u32_e32 v64, vcc, s8, v4
	s_mov_b32 s8, 0x54000
	s_nop 0
	v_addc_co_u32_e32 v65, vcc, 0, v5, vcc
	s_waitcnt vmcnt(62) lgkmcnt(0)
	v_fmac_f32_e32 v60, v61, v62
	v_cvt_pk_bf16_f32 v8, v60, s0
	v_fmac_f32_e32 v59, v60, v63
	v_add_co_u32_e32 v60, vcc, s47, v4
	global_store_short v[64:65], v8, off
	v_cvt_pk_bf16_f32 v8, v59, s0
	v_addc_co_u32_e32 v61, vcc, 0, v5, vcc
	global_store_short v[60:61], v8, off
	ds_read2st64_b32 v[60:61], v11 offset0:20 offset1:21
	v_add_co_u32_e32 v62, vcc, s8, v4
	s_mov_b32 s8, 0x5c000
	s_nop 0
	v_addc_co_u32_e32 v63, vcc, 0, v5, vcc
	s_waitcnt vmcnt(62) lgkmcnt(0)
	v_fmac_f32_e32 v58, v59, v60
	v_cvt_pk_bf16_f32 v8, v58, s0
	v_fmac_f32_e32 v57, v58, v61
	v_add_co_u32_e32 v58, vcc, s48, v4
	global_store_short v[62:63], v8, off
	v_cvt_pk_bf16_f32 v8, v57, s0
	v_addc_co_u32_e32 v59, vcc, 0, v5, vcc
	global_store_short v[58:59], v8, off
	ds_read2st64_b32 v[58:59], v11 offset0:22 offset1:23
	v_add_co_u32_e32 v60, vcc, s8, v4
	s_mov_b32 s8, 0x64000
	s_nop 0
	v_addc_co_u32_e32 v61, vcc, 0, v5, vcc
	s_waitcnt vmcnt(62) lgkmcnt(0)
	v_fmac_f32_e32 v56, v57, v58
	v_cvt_pk_bf16_f32 v8, v56, s0
	v_fmac_f32_e32 v55, v56, v59
	v_add_co_u32_e32 v56, vcc, s49, v4
	global_store_short v[60:61], v8, off
	v_cvt_pk_bf16_f32 v8, v55, s0
	v_addc_co_u32_e32 v57, vcc, 0, v5, vcc
	global_store_short v[56:57], v8, off
	ds_read2st64_b32 v[56:57], v11 offset0:24 offset1:25
	v_add_co_u32_e32 v58, vcc, s8, v4
	s_mov_b32 s8, 0x6c000
	s_nop 0
	v_addc_co_u32_e32 v59, vcc, 0, v5, vcc
	s_waitcnt vmcnt(62) lgkmcnt(0)
	v_fmac_f32_e32 v54, v55, v56
	v_cvt_pk_bf16_f32 v8, v54, s0
	v_fmac_f32_e32 v53, v54, v57
	v_add_co_u32_e32 v54, vcc, s50, v4
	global_store_short v[58:59], v8, off
	v_cvt_pk_bf16_f32 v8, v53, s0
	v_addc_co_u32_e32 v55, vcc, 0, v5, vcc
	global_store_short v[54:55], v8, off
	ds_read2st64_b32 v[54:55], v11 offset0:26 offset1:27
	v_add_co_u32_e32 v56, vcc, s8, v4
	s_mov_b32 s8, 0x74000
	s_nop 0
	v_addc_co_u32_e32 v57, vcc, 0, v5, vcc
	s_waitcnt vmcnt(62) lgkmcnt(0)
	v_fmac_f32_e32 v52, v53, v54
	v_cvt_pk_bf16_f32 v8, v52, s0
	v_fmac_f32_e32 v51, v52, v55
	v_add_co_u32_e32 v52, vcc, s51, v4
	global_store_short v[56:57], v8, off
	v_cvt_pk_bf16_f32 v8, v51, s0
	v_addc_co_u32_e32 v53, vcc, 0, v5, vcc
	global_store_short v[52:53], v8, off
	ds_read2st64_b32 v[52:53], v11 offset0:28 offset1:29
	v_add_co_u32_e32 v54, vcc, s8, v4
	s_mov_b32 s8, 0x7c000
	s_nop 0
	v_addc_co_u32_e32 v55, vcc, 0, v5, vcc
	s_waitcnt vmcnt(62) lgkmcnt(0)
	v_fmac_f32_e32 v50, v51, v52
	v_cvt_pk_bf16_f32 v8, v50, s0
	v_fmac_f32_e32 v49, v50, v53
	v_add_co_u32_e32 v50, vcc, s52, v4
	global_store_short v[54:55], v8, off
	v_cvt_pk_bf16_f32 v8, v49, s0
	v_addc_co_u32_e32 v51, vcc, 0, v5, vcc
	global_store_short v[50:51], v8, off
	ds_read2st64_b32 v[50:51], v11 offset0:30 offset1:31
	v_add_co_u32_e32 v52, vcc, s8, v4
	s_mov_b32 s8, 0x84000
	s_nop 0
	v_addc_co_u32_e32 v53, vcc, 0, v5, vcc
	s_waitcnt vmcnt(62) lgkmcnt(0)
; DI bf16_t f2bf(float f) { return (bf16_t)(pk2(f, 0.f) & 0xffffu); }
; DI void gla_scan(const Params& p, int G, LAS unsigned char* lds) {
;     ...
; #pragma unroll
;             for (int j2 = 0; j2 < 64; ++j2) { sp[(size_t)(n0 + j2) * 8192] = f2bf(st); st = dl[(n0 + j2) * 64 + k] * st + dv[j2]; } }
	v_fmac_f32_e32 v48, v49, v50
	v_cvt_pk_bf16_f32 v8, v48, s0
	v_fmac_f32_e32 v47, v48, v51
	v_add_co_u32_e32 v48, vcc, s53, v4
	global_store_short v[52:53], v8, off
	v_cvt_pk_bf16_f32 v8, v47, s0
	v_addc_co_u32_e32 v49, vcc, 0, v5, vcc
	global_store_short v[48:49], v8, off
	ds_read2st64_b32 v[48:49], v11 offset0:32 offset1:33
	v_add_co_u32_e32 v50, vcc, s8, v4
	s_mov_b32 s8, 0x8c000
	s_nop 0
	v_addc_co_u32_e32 v51, vcc, 0, v5, vcc
	s_waitcnt vmcnt(62) lgkmcnt(0)
	v_fmac_f32_e32 v46, v47, v48
	v_cvt_pk_bf16_f32 v8, v46, s0
	v_fmac_f32_e32 v45, v46, v49
	v_add_co_u32_e32 v46, vcc, s55, v4
	global_store_short v[50:51], v8, off
	v_cvt_pk_bf16_f32 v8, v45, s0
	v_addc_co_u32_e32 v47, vcc, 0, v5, vcc
	global_store_short v[46:47], v8, off
	ds_read2st64_b32 v[46:47], v11 offset0:34 offset1:35
	v_add_co_u32_e32 v48, vcc, s8, v4
	s_mov_b32 s8, 0x94000
	s_nop 0
	v_addc_co_u32_e32 v49, vcc, 0, v5, vcc
	s_waitcnt vmcnt(62) lgkmcnt(0)
	v_fmac_f32_e32 v44, v45, v46
	v_cvt_pk_bf16_f32 v8, v44, s0
	v_fmac_f32_e32 v43, v44, v47
	v_add_co_u32_e32 v44, vcc, s56, v4
	global_store_short v[48:49], v8, off
	v_cvt_pk_bf16_f32 v8, v43, s0
	v_addc_co_u32_e32 v45, vcc, 0, v5, vcc
	global_store_short v[44:45], v8, off
	ds_read2st64_b32 v[44:45], v11 offset0:36 offset1:37
	v_add_co_u32_e32 v46, vcc, s8, v4
	s_mov_b32 s8, 0x9c000
	s_nop 0
	v_addc_co_u32_e32 v47, vcc, 0, v5, vcc
	s_waitcnt vmcnt(62) lgkmcnt(0)
	v_fmac_f32_e32 v42, v43, v44
	v_cvt_pk_bf16_f32 v8, v42, s0
	v_fmac_f32_e32 v41, v42, v45
	v_add_co_u32_e32 v42, vcc, s57, v4
	global_store_short v[46:47], v8, off
	v_cvt_pk_bf16_f32 v8, v41, s0
	v_addc_co_u32_e32 v43, vcc, 0, v5, vcc
	global_store_short v[42:43], v8, off
	ds_read2st64_b32 v[42:43], v11 offset0:38 offset1:39
	v_add_co_u32_e32 v44, vcc, s8, v4
	s_mov_b32 s8, 0xa4000
	s_nop 0
	v_addc_co_u32_e32 v45, vcc, 0, v5, vcc
	s_waitcnt vmcnt(62) lgkmcnt(0)
	v_fmac_f32_e32 v40, v41, v42
	v_cvt_pk_bf16_f32 v8, v40, s0
	v_fmac_f32_e32 v39, v40, v43
	v_add_co_u32_e32 v40, vcc, s58, v4
	global_store_short v[44:45], v8, off
	v_cvt_pk_bf16_f32 v8, v39, s0
	v_addc_co_u32_e32 v41, vcc, 0, v5, vcc
	global_store_short v[40:41], v8, off
	ds_read2st64_b32 v[40:41], v11 offset0:40 offset1:41
	v_add_co_u32_e32 v42, vcc, s8, v4
	s_mov_b32 s8, 0xac000
	s_nop 0
	v_addc_co_u32_e32 v43, vcc, 0, v5, vcc
	s_waitcnt vmcnt(62) lgkmcnt(0)
	v_fmac_f32_e32 v38, v39, v40
	v_cvt_pk_bf16_f32 v8, v38, s0
	v_fmac_f32_e32 v37, v38, v41
	v_add_co_u32_e32 v38, vcc, s59, v4
	global_store_short v[42:43], v8, off
	v_cvt_pk_bf16_f32 v8, v37, s0
	v_addc_co_u32_e32 v39, vcc, 0, v5, vcc
	global_store_short v[38:39], v8, off
	ds_read2st64_b32 v[38:39], v11 offset0:42 offset1:43
	v_add_co_u32_e32 v40, vcc, s8, v4
	s_mov_b32 s8, 0xb4000
	s_nop 0
	v_addc_co_u32_e32 v41, vcc, 0, v5, vcc
	s_waitcnt vmcnt(62) lgkmcnt(0)
	v_fmac_f32_e32 v36, v37, v38
	v_cvt_pk_bf16_f32 v8, v36, s0
	v_fmac_f32_e32 v35, v36, v39
	v_add_co_u32_e32 v36, vcc, s60, v4
	global_store_short v[40:41], v8, off
	v_cvt_pk_bf16_f32 v8, v35, s0
	v_addc_co_u32_e32 v37, vcc, 0, v5, vcc
	global_store_short v[36:37], v8, off
	ds_read2st64_b32 v[36:37], v11 offset0:44 offset1:45
	v_add_co_u32_e32 v38, vcc, s8, v4
	s_mov_b32 s8, 0xbc000
	s_nop 0
	v_addc_co_u32_e32 v39, vcc, 0, v5, vcc
	s_waitcnt vmcnt(62) lgkmcnt(0)
	v_fmac_f32_e32 v34, v35, v36
	v_cvt_pk_bf16_f32 v8, v34, s0
	v_fmac_f32_e32 v33, v34, v37
	v_add_co_u32_e32 v34, vcc, s61, v4
	global_store_short v[38:39], v8, off
	v_cvt_pk_bf16_f32 v8, v33, s0
	v_addc_co_u32_e32 v35, vcc, 0, v5, vcc
	global_store_short v[34:35], v8, off
	ds_read2st64_b32 v[34:35], v11 offset0:46 offset1:47
	v_add_co_u32_e32 v36, vcc, s8, v4
	s_mov_b32 s8, 0xc4000
	s_nop 0
	v_addc_co_u32_e32 v37, vcc, 0, v5, vcc
	s_waitcnt vmcnt(62) lgkmcnt(0)
	v_fmac_f32_e32 v32, v33, v34
	v_cvt_pk_bf16_f32 v8, v32, s0
	v_fmac_f32_e32 v31, v32, v35
	v_add_co_u32_e32 v32, vcc, s62, v4
	global_store_short v[36:37], v8, off
	v_cvt_pk_bf16_f32 v8, v31, s0
	v_addc_co_u32_e32 v33, vcc, 0, v5, vcc
	global_store_short v[32:33], v8, off
	ds_read2st64_b32 v[32:33], v11 offset0:48 offset1:49
	v_add_co_u32_e32 v34, vcc, s8, v4
	s_mov_b32 s8, 0xcc000
	s_nop 0
	v_addc_co_u32_e32 v35, vcc, 0, v5, vcc
	s_waitcnt vmcnt(62) lgkmcnt(0)
	v_fmac_f32_e32 v30, v31, v32
	v_cvt_pk_bf16_f32 v8, v30, s0
	v_fmac_f32_e32 v29, v30, v33
	v_add_co_u32_e32 v30, vcc, s63, v4
	global_store_short v[34:35], v8, off
	v_cvt_pk_bf16_f32 v8, v29, s0
	v_addc_co_u32_e32 v31, vcc, 0, v5, vcc
	global_store_short v[30:31], v8, off
	ds_read2st64_b32 v[30:31], v11 offset0:50 offset1:51
	v_add_co_u32_e32 v32, vcc, s8, v4
	s_mov_b32 s8, 0xd4000
	s_nop 0
	v_addc_co_u32_e32 v33, vcc, 0, v5, vcc
	s_waitcnt vmcnt(62) lgkmcnt(0)
	v_fmac_f32_e32 v28, v29, v30
	v_cvt_pk_bf16_f32 v8, v28, s0
	v_fmac_f32_e32 v27, v28, v31
	v_add_co_u32_e32 v28, vcc, s64, v4
	global_store_short v[32:33], v8, off
	v_cvt_pk_bf16_f32 v8, v27, s0
	v_addc_co_u32_e32 v29, vcc, 0, v5, vcc
	global_store_short v[28:29], v8, off
	ds_read2st64_b32 v[28:29], v11 offset0:52 offset1:53
	v_add_co_u32_e32 v30, vcc, s8, v4
	s_mov_b32 s8, 0xdc000
	s_nop 0
	v_addc_co_u32_e32 v31, vcc, 0, v5, vcc
	s_waitcnt vmcnt(62) lgkmcnt(0)
	v_fmac_f32_e32 v26, v27, v28
	v_cvt_pk_bf16_f32 v8, v26, s0
	v_fmac_f32_e32 v25, v26, v29
	v_add_co_u32_e32 v26, vcc, s65, v4
	global_store_short v[30:31], v8, off
	v_cvt_pk_bf16_f32 v8, v25, s0
	v_addc_co_u32_e32 v27, vcc, 0, v5, vcc
	global_store_short v[26:27], v8, off
	ds_read2st64_b32 v[26:27], v11 offset0:54 offset1:55
	v_add_co_u32_e32 v28, vcc, s8, v4
	s_mov_b32 s8, 0xe4000
	s_nop 0
	v_addc_co_u32_e32 v29, vcc, 0, v5, vcc
	s_waitcnt vmcnt(62) lgkmcnt(0)
; DI bf16_t f2bf(float f) { return (bf16_t)(pk2(f, 0.f) & 0xffffu); }
; DI void gla_scan(const Params& p, int G, LAS unsigned char* lds) {
;     ...
;         for (int n0 = 0; n0 < 128; n0 += 64) { float dv[64];
; #pragma unroll
;             for (int j2 = 0; j2 < 64; ++j2) dv[j2] = __builtin_nontemporal_load(dp + (size_t)(n0 + j2) * 8192);
; #pragma unroll
;             for (int j2 = 0; j2 < 64; ++j2) { sp[(size_t)(n0 + j2) * 8192] = f2bf(st); st = dl[(n0 + j2) * 64 + k] * st + dv[j2]; } }
	v_fmac_f32_e32 v24, v25, v26
	v_cvt_pk_bf16_f32 v8, v24, s0
	v_fmac_f32_e32 v23, v24, v27
	v_add_co_u32_e32 v24, vcc, s66, v4
	global_store_short v[28:29], v8, off
	v_cvt_pk_bf16_f32 v8, v23, s0
	v_addc_co_u32_e32 v25, vcc, 0, v5, vcc
	global_store_short v[24:25], v8, off
	ds_read2st64_b32 v[24:25], v11 offset0:56 offset1:57
	v_add_co_u32_e32 v26, vcc, s8, v4
	s_mov_b32 s8, 0xec000
	s_nop 0
	v_addc_co_u32_e32 v27, vcc, 0, v5, vcc
	s_waitcnt vmcnt(62) lgkmcnt(0)
	v_fmac_f32_e32 v22, v23, v24
	v_cvt_pk_bf16_f32 v8, v22, s0
	v_fmac_f32_e32 v21, v22, v25
	v_add_co_u32_e32 v22, vcc, s67, v4
	global_store_short v[26:27], v8, off
	v_cvt_pk_bf16_f32 v8, v21, s0
	v_addc_co_u32_e32 v23, vcc, 0, v5, vcc
	global_store_short v[22:23], v8, off
	ds_read2st64_b32 v[22:23], v11 offset0:58 offset1:59
	v_add_co_u32_e32 v24, vcc, s8, v4
	s_mov_b32 s8, 0xf4000
	s_nop 0
	v_addc_co_u32_e32 v25, vcc, 0, v5, vcc
	s_waitcnt vmcnt(62) lgkmcnt(0)
	v_fmac_f32_e32 v20, v21, v22
	v_cvt_pk_bf16_f32 v8, v20, s0
	v_fmac_f32_e32 v18, v20, v23
	v_add_co_u32_e32 v20, vcc, s68, v4
	global_store_short v[24:25], v8, off
	v_cvt_pk_bf16_f32 v8, v18, s0
	v_addc_co_u32_e32 v21, vcc, 0, v5, vcc
	global_store_short v[20:21], v8, off
	ds_read2st64_b32 v[20:21], v11 offset0:60 offset1:61
	v_add_co_u32_e32 v22, vcc, s8, v4
	s_mov_b32 s8, 0xfc000
	s_nop 0
	v_addc_co_u32_e32 v23, vcc, 0, v5, vcc
	s_waitcnt vmcnt(62) lgkmcnt(0)
	v_fmac_f32_e32 v17, v18, v20
	v_cvt_pk_bf16_f32 v8, v17, s0
	v_fmac_f32_e32 v9, v17, v21
	v_add_co_u32_e32 v20, vcc, s69, v4
	global_store_short v[22:23], v8, off
	v_cvt_pk_bf16_f32 v8, v9, s0
	v_addc_co_u32_e32 v21, vcc, 0, v5, vcc
	global_store_short v[20:21], v8, off
	ds_read2st64_b32 v[20:21], v11 offset0:62 offset1:63
	v_add_co_u32_e32 v8, vcc, s8, v4
	s_mov_b32 s8, 0x200000
	s_waitcnt vmcnt(62) lgkmcnt(0)
	v_fmac_f32_e32 v0, v9, v20
	v_cvt_pk_bf16_f32 v17, v0, s0
	v_addc_co_u32_e32 v9, vcc, 0, v5, vcc
	global_store_short v[8:9], v17, off
	v_add_co_u32_e32 v8, vcc, s8, v6
	s_mov_b32 s8, 0x208000
	s_nop 0
	v_addc_co_u32_e32 v9, vcc, 0, v7, vcc
	v_fmac_f32_e32 v19, v0, v21
	global_load_dword v0, v[8:9], off nt
	v_add_co_u32_e32 v8, vcc, s8, v6
	s_mov_b32 s8, 0x210000
	s_nop 0
	v_addc_co_u32_e32 v9, vcc, 0, v7, vcc
	global_load_dword v77, v[8:9], off nt
	v_add_co_u32_e32 v8, vcc, s8, v6
	s_mov_b32 s8, 0x218000
	s_nop 0
	v_addc_co_u32_e32 v9, vcc, 0, v7, vcc
	global_load_dword v75, v[8:9], off nt
	v_add_co_u32_e32 v8, vcc, s8, v6
	s_mov_b32 s8, 0x220000
	s_nop 0
	v_addc_co_u32_e32 v9, vcc, 0, v7, vcc
	global_load_dword v76, v[8:9], off nt
	v_add_co_u32_e32 v8, vcc, s8, v6
	s_mov_b32 s8, 0x228000
	s_nop 0
	v_addc_co_u32_e32 v9, vcc, 0, v7, vcc
	global_load_dword v73, v[8:9], off nt
	v_add_co_u32_e32 v8, vcc, s8, v6
	s_mov_b32 s8, 0x230000
	s_nop 0
	v_addc_co_u32_e32 v9, vcc, 0, v7, vcc
	global_load_dword v74, v[8:9], off nt
	v_add_co_u32_e32 v8, vcc, s8, v6
	s_mov_b32 s8, 0x238000
	s_nop 0
	v_addc_co_u32_e32 v9, vcc, 0, v7, vcc
	global_load_dword v71, v[8:9], off nt
	v_add_co_u32_e32 v8, vcc, s8, v6
	s_mov_b32 s8, 0x240000
	s_nop 0
	v_addc_co_u32_e32 v9, vcc, 0, v7, vcc
	global_load_dword v72, v[8:9], off nt
	v_add_co_u32_e32 v8, vcc, s8, v6
	s_mov_b32 s8, 0x248000
	s_nop 0
	v_addc_co_u32_e32 v9, vcc, 0, v7, vcc
	global_load_dword v68, v[8:9], off nt
	v_add_co_u32_e32 v8, vcc, s8, v6
	s_mov_b32 s8, 0x250000
	s_nop 0
	v_addc_co_u32_e32 v9, vcc, 0, v7, vcc
	global_load_dword v69, v[8:9], off nt
	v_add_co_u32_e32 v8, vcc, s8, v6
	s_mov_b32 s8, 0x258000
	s_nop 0
	v_addc_co_u32_e32 v9, vcc, 0, v7, vcc
	global_load_dword v62, v[8:9], off nt
	v_add_co_u32_e32 v8, vcc, s8, v6
	s_mov_b32 s8, 0x260000
	s_nop 0
	v_addc_co_u32_e32 v9, vcc, 0, v7, vcc
	global_load_dword v63, v[8:9], off nt
	v_add_co_u32_e32 v8, vcc, s8, v6
	s_mov_b32 s8, 0x268000
	s_nop 0
	v_addc_co_u32_e32 v9, vcc, 0, v7, vcc
	global_load_dword v59, v[8:9], off nt
	v_add_co_u32_e32 v8, vcc, s8, v6
	s_mov_b32 s8, 0x270000
	s_nop 0
	v_addc_co_u32_e32 v9, vcc, 0, v7, vcc
	global_load_dword v70, v[8:9], off nt
	v_add_co_u32_e32 v8, vcc, s8, v6
	s_mov_b32 s8, 0x278000
	s_nop 0
	v_addc_co_u32_e32 v9, vcc, 0, v7, vcc
	global_load_dword v66, v[8:9], off nt
	v_add_co_u32_e32 v8, vcc, s8, v6
	s_mov_b32 s8, 0x280000
	s_nop 0
	v_addc_co_u32_e32 v9, vcc, 0, v7, vcc
	global_load_dword v67, v[8:9], off nt
	v_add_co_u32_e32 v8, vcc, s8, v6
	s_mov_b32 s8, 0x288000
	s_nop 0
	v_addc_co_u32_e32 v9, vcc, 0, v7, vcc
	global_load_dword v64, v[8:9], off nt
	v_add_co_u32_e32 v8, vcc, s8, v6
	s_mov_b32 s8, 0x290000
	s_nop 0
	v_addc_co_u32_e32 v9, vcc, 0, v7, vcc
	global_load_dword v65, v[8:9], off nt
	v_add_co_u32_e32 v8, vcc, s8, v6
	s_mov_b32 s8, 0x298000
	s_nop 0
	v_addc_co_u32_e32 v9, vcc, 0, v7, vcc
	global_load_dword v60, v[8:9], off nt
	v_add_co_u32_e32 v8, vcc, s8, v6
	s_mov_b32 s8, 0x2a0000
	s_nop 0
	v_addc_co_u32_e32 v9, vcc, 0, v7, vcc
	global_load_dword v61, v[8:9], off nt
	v_add_co_u32_e32 v8, vcc, s8, v6
	s_mov_b32 s8, 0x2a8000
	s_nop 0
	v_addc_co_u32_e32 v9, vcc, 0, v7, vcc
	global_load_dword v57, v[8:9], off nt
	v_add_co_u32_e32 v8, vcc, s8, v6
	s_mov_b32 s8, 0x2b0000
	s_nop 0
	v_addc_co_u32_e32 v9, vcc, 0, v7, vcc
	global_load_dword v58, v[8:9], off nt
	v_add_co_u32_e32 v8, vcc, s8, v6
	s_mov_b32 s8, 0x2b8000
	s_nop 0
	v_addc_co_u32_e32 v9, vcc, 0, v7, vcc
	global_load_dword v55, v[8:9], off nt
	v_add_co_u32_e32 v8, vcc, s8, v6
	s_mov_b32 s8, 0x2c0000
	s_nop 0
	v_addc_co_u32_e32 v9, vcc, 0, v7, vcc
	global_load_dword v56, v[8:9], off nt
	v_add_co_u32_e32 v8, vcc, s8, v6
	s_mov_b32 s8, 0x2c8000
	s_nop 0
	v_addc_co_u32_e32 v9, vcc, 0, v7, vcc
	global_load_dword v53, v[8:9], off nt
	v_add_co_u32_e32 v8, vcc, s8, v6
; DI bf16_t f2bf(float f) { return (bf16_t)(pk2(f, 0.f) & 0xffffu); }
; DI void gla_scan(const Params& p, int G, LAS unsigned char* lds) {
;     ...
;         for (int n0 = 0; n0 < 128; n0 += 64) { float dv[64];
; #pragma unroll
;             for (int j2 = 0; j2 < 64; ++j2) dv[j2] = __builtin_nontemporal_load(dp + (size_t)(n0 + j2) * 8192);
; #pragma unroll
;             for (int j2 = 0; j2 < 64; ++j2) { sp[(size_t)(n0 + j2) * 8192] = f2bf(st); st = dl[(n0 + j2) * 64 + k] * st + dv[j2]; } }
	s_mov_b32 s8, 0x2d0000
	s_nop 0
	v_addc_co_u32_e32 v9, vcc, 0, v7, vcc
	global_load_dword v54, v[8:9], off nt
	v_add_co_u32_e32 v8, vcc, s8, v6
	s_mov_b32 s8, 0x2d8000
	s_nop 0
	v_addc_co_u32_e32 v9, vcc, 0, v7, vcc
	global_load_dword v51, v[8:9], off nt
	v_add_co_u32_e32 v8, vcc, s8, v6
	s_mov_b32 s8, 0x2e0000
	s_nop 0
	v_addc_co_u32_e32 v9, vcc, 0, v7, vcc
	global_load_dword v52, v[8:9], off nt
	v_add_co_u32_e32 v8, vcc, s8, v6
	s_mov_b32 s8, 0x2e8000
	s_nop 0
	v_addc_co_u32_e32 v9, vcc, 0, v7, vcc
	global_load_dword v49, v[8:9], off nt
	v_add_co_u32_e32 v8, vcc, s8, v6
	s_mov_b32 s8, 0x2f0000
	s_nop 0
	v_addc_co_u32_e32 v9, vcc, 0, v7, vcc
	global_load_dword v50, v[8:9], off nt
	v_add_co_u32_e32 v8, vcc, s8, v6
	s_mov_b32 s8, 0x2f8000
	s_nop 0
	v_addc_co_u32_e32 v9, vcc, 0, v7, vcc
	global_load_dword v47, v[8:9], off nt
	v_add_co_u32_e32 v8, vcc, s8, v6
	s_mov_b32 s8, 0x300000
	s_nop 0
	v_addc_co_u32_e32 v9, vcc, 0, v7, vcc
	global_load_dword v48, v[8:9], off nt
	v_add_co_u32_e32 v8, vcc, s8, v6
	s_mov_b32 s8, 0x308000
	s_nop 0
	v_addc_co_u32_e32 v9, vcc, 0, v7, vcc
	global_load_dword v45, v[8:9], off nt
	v_add_co_u32_e32 v8, vcc, s8, v6
	s_mov_b32 s8, 0x310000
	s_nop 0
	v_addc_co_u32_e32 v9, vcc, 0, v7, vcc
	global_load_dword v46, v[8:9], off nt
	v_add_co_u32_e32 v8, vcc, s8, v6
	s_mov_b32 s8, 0x318000
	s_nop 0
	v_addc_co_u32_e32 v9, vcc, 0, v7, vcc
	global_load_dword v43, v[8:9], off nt
	v_add_co_u32_e32 v8, vcc, s8, v6
	s_mov_b32 s8, 0x320000
	s_nop 0
	v_addc_co_u32_e32 v9, vcc, 0, v7, vcc
	global_load_dword v44, v[8:9], off nt
	v_add_co_u32_e32 v8, vcc, s8, v6
	s_mov_b32 s8, 0x328000
	s_nop 0
	v_addc_co_u32_e32 v9, vcc, 0, v7, vcc
	global_load_dword v41, v[8:9], off nt
	v_add_co_u32_e32 v8, vcc, s8, v6
	s_mov_b32 s8, 0x330000
	s_nop 0
	v_addc_co_u32_e32 v9, vcc, 0, v7, vcc
	global_load_dword v42, v[8:9], off nt
	v_add_co_u32_e32 v8, vcc, s8, v6
	s_mov_b32 s8, 0x338000
	s_nop 0
	v_addc_co_u32_e32 v9, vcc, 0, v7, vcc
	global_load_dword v39, v[8:9], off nt
	v_add_co_u32_e32 v8, vcc, s8, v6
	s_mov_b32 s8, 0x340000
	s_nop 0
	v_addc_co_u32_e32 v9, vcc, 0, v7, vcc
	global_load_dword v40, v[8:9], off nt
	v_add_co_u32_e32 v8, vcc, s8, v6
	s_mov_b32 s8, 0x348000
	s_nop 0
	v_addc_co_u32_e32 v9, vcc, 0, v7, vcc
	global_load_dword v37, v[8:9], off nt
	v_add_co_u32_e32 v8, vcc, s8, v6
	s_mov_b32 s8, 0x350000
	s_nop 0
	v_addc_co_u32_e32 v9, vcc, 0, v7, vcc
	global_load_dword v38, v[8:9], off nt
	v_add_co_u32_e32 v8, vcc, s8, v6
	s_mov_b32 s8, 0x358000
	s_nop 0
	v_addc_co_u32_e32 v9, vcc, 0, v7, vcc
	global_load_dword v35, v[8:9], off nt
	v_add_co_u32_e32 v8, vcc, s8, v6
	s_mov_b32 s8, 0x360000
	s_nop 0
	v_addc_co_u32_e32 v9, vcc, 0, v7, vcc
	global_load_dword v36, v[8:9], off nt
	v_add_co_u32_e32 v8, vcc, s8, v6
	s_mov_b32 s8, 0x368000
	s_nop 0
	v_addc_co_u32_e32 v9, vcc, 0, v7, vcc
	global_load_dword v33, v[8:9], off nt
	v_add_co_u32_e32 v8, vcc, s8, v6
	s_mov_b32 s8, 0x370000
	s_nop 0
	v_addc_co_u32_e32 v9, vcc, 0, v7, vcc
	global_load_dword v34, v[8:9], off nt
	v_add_co_u32_e32 v8, vcc, s8, v6
	s_mov_b32 s8, 0x378000
	s_nop 0
	v_addc_co_u32_e32 v9, vcc, 0, v7, vcc
	global_load_dword v30, v[8:9], off nt
	v_add_co_u32_e32 v8, vcc, s8, v6
	s_mov_b32 s8, 0x380000
	s_nop 0
	v_addc_co_u32_e32 v9, vcc, 0, v7, vcc
	global_load_dword v31, v[8:9], off nt
	v_add_co_u32_e32 v8, vcc, s8, v6
	s_mov_b32 s8, 0x388000
	s_nop 0
	v_addc_co_u32_e32 v9, vcc, 0, v7, vcc
	global_load_dword v24, v[8:9], off nt
	v_add_co_u32_e32 v8, vcc, s8, v6
	s_mov_b32 s8, 0x390000
	s_nop 0
	v_addc_co_u32_e32 v9, vcc, 0, v7, vcc
	global_load_dword v26, v[8:9], off nt
	v_add_co_u32_e32 v8, vcc, s8, v6
	s_mov_b32 s8, 0x398000
	s_nop 0
	v_addc_co_u32_e32 v9, vcc, 0, v7, vcc
	global_load_dword v22, v[8:9], off nt
	v_add_co_u32_e32 v8, vcc, s8, v6
	s_mov_b32 s8, 0x3a0000
	s_nop 0
	v_addc_co_u32_e32 v9, vcc, 0, v7, vcc
	global_load_dword v28, v[8:9], off nt
	v_add_co_u32_e32 v8, vcc, s8, v6
	s_mov_b32 s8, 0x3a8000
	s_nop 0
	v_addc_co_u32_e32 v9, vcc, 0, v7, vcc
	global_load_dword v29, v[8:9], off nt
	v_add_co_u32_e32 v8, vcc, s8, v6
	s_mov_b32 s8, 0x3b0000
	s_nop 0
	v_addc_co_u32_e32 v9, vcc, 0, v7, vcc
	global_load_dword v32, v[8:9], off nt
	v_add_co_u32_e32 v8, vcc, s8, v6
	s_mov_b32 s8, 0x3b8000
	s_nop 0
	v_addc_co_u32_e32 v9, vcc, 0, v7, vcc
	global_load_dword v25, v[8:9], off nt
	v_add_co_u32_e32 v8, vcc, s8, v6
	s_mov_b32 s8, 0x3c0000
	s_nop 0
	v_addc_co_u32_e32 v9, vcc, 0, v7, vcc
	global_load_dword v27, v[8:9], off nt
	v_add_co_u32_e32 v8, vcc, s8, v6
	s_mov_b32 s8, 0x3c8000
	s_nop 0
	v_addc_co_u32_e32 v9, vcc, 0, v7, vcc
	global_load_dword v20, v[8:9], off nt
	v_add_co_u32_e32 v8, vcc, s8, v6
	s_mov_b32 s8, 0x3d0000
	s_nop 0
	v_addc_co_u32_e32 v9, vcc, 0, v7, vcc
	global_load_dword v21, v[8:9], off nt
	v_add_co_u32_e32 v8, vcc, s8, v6
	s_mov_b32 s8, 0x3d8000
	s_nop 0
	v_addc_co_u32_e32 v9, vcc, 0, v7, vcc
	global_load_dword v18, v[8:9], off nt
	v_add_co_u32_e32 v8, vcc, s8, v6
	s_mov_b32 s8, 0x3e0000
	s_nop 0
	v_addc_co_u32_e32 v9, vcc, 0, v7, vcc
	global_load_dword v17, v[8:9], off nt
	v_add_co_u32_e32 v8, vcc, s8, v6
	s_mov_b32 s8, 0x3e8000
	s_nop 0
	v_addc_co_u32_e32 v9, vcc, 0, v7, vcc
	v_add_co_u32_e32 v78, vcc, s8, v6
	s_mov_b32 s8, 0x3f0000
	s_nop 0
	v_addc_co_u32_e32 v79, vcc, 0, v7, vcc
	v_add_co_u32_e32 v6, vcc, s8, v6
	global_load_dword v9, v[8:9], off nt
	s_nop 0
	v_addc_co_u32_e32 v7, vcc, 0, v7, vcc
	global_load_dword v23, v[6:7], off nt
	v_add_co_u32_e32 v6, vcc, s70, v4
	global_load_dword v8, v[78:79], off nt
	v_cvt_pk_bf16_f32 v78, v19, s0
	v_addc_co_u32_e32 v7, vcc, 0, v5, vcc
	global_store_short v[6:7], v78, off
	ds_read2st64_b32 v[6:7], v11 offset0:64 offset1:65
	s_mov_b32 s8, 0x104000
	v_add_co_u32_e32 v78, vcc, s8, v4
	s_mov_b32 s8, 0x10c000
	s_waitcnt vmcnt(62) lgkmcnt(0)
; DI bf16_t f2bf(float f) { return (bf16_t)(pk2(f, 0.f) & 0xffffu); }
; DI void gla_scan(const Params& p, int G, LAS unsigned char* lds) {
;     ...
; #pragma unroll
;             for (int j2 = 0; j2 < 64; ++j2) { sp[(size_t)(n0 + j2) * 8192] = f2bf(st); st = dl[(n0 + j2) * 64 + k] * st + dv[j2]; } }
	v_fmac_f32_e32 v0, v19, v6
	v_cvt_pk_bf16_f32 v6, v0, s0
	v_addc_co_u32_e32 v79, vcc, 0, v5, vcc
	global_store_short v[78:79], v6, off
	v_fmac_f32_e32 v77, v0, v7
	v_add_co_u32_e32 v6, vcc, s71, v4
	v_cvt_pk_bf16_f32 v0, v77, s0
	s_nop 0
	v_addc_co_u32_e32 v7, vcc, 0, v5, vcc
	global_store_short v[6:7], v0, off
	ds_read2st64_b32 v[6:7], v11 offset0:66 offset1:67
	v_add_co_u32_e32 v78, vcc, s8, v4
	s_mov_b32 s8, 0x114000
	s_nop 0
	v_addc_co_u32_e32 v79, vcc, 0, v5, vcc
	s_waitcnt vmcnt(62) lgkmcnt(0)
	v_fmac_f32_e32 v75, v77, v6
	v_cvt_pk_bf16_f32 v0, v75, s0
	v_fmac_f32_e32 v76, v75, v7
	v_add_co_u32_e32 v6, vcc, s72, v4
	global_store_short v[78:79], v0, off
	v_cvt_pk_bf16_f32 v0, v76, s0
	v_addc_co_u32_e32 v7, vcc, 0, v5, vcc
	global_store_short v[6:7], v0, off
	ds_read2st64_b32 v[6:7], v11 offset0:68 offset1:69
	s_waitcnt vmcnt(62) lgkmcnt(0)
	v_fmac_f32_e32 v73, v76, v6
	v_add_co_u32_e32 v76, vcc, s8, v4
	v_cvt_pk_bf16_f32 v0, v73, s0
	s_nop 0
	v_addc_co_u32_e32 v77, vcc, 0, v5, vcc
	v_fmac_f32_e32 v74, v73, v7
	v_add_co_u32_e32 v6, vcc, s73, v4
	global_store_short v[76:77], v0, off
	v_cvt_pk_bf16_f32 v0, v74, s0
	v_addc_co_u32_e32 v7, vcc, 0, v5, vcc
	global_store_short v[6:7], v0, off
	ds_read2st64_b32 v[6:7], v11 offset0:70 offset1:71
	s_mov_b32 s8, 0x11c000
	s_waitcnt vmcnt(62) lgkmcnt(0)
	v_fmac_f32_e32 v71, v74, v6
	v_add_co_u32_e32 v74, vcc, s8, v4
	v_cvt_pk_bf16_f32 v0, v71, s0
	s_nop 0
	v_addc_co_u32_e32 v75, vcc, 0, v5, vcc
	v_fmac_f32_e32 v72, v71, v7
	v_add_co_u32_e32 v6, vcc, s78, v4
	global_store_short v[74:75], v0, off
	v_cvt_pk_bf16_f32 v0, v72, s0
	v_addc_co_u32_e32 v7, vcc, 0, v5, vcc
	global_store_short v[6:7], v0, off
	ds_read2st64_b32 v[6:7], v11 offset0:72 offset1:73
	s_mov_b32 s8, 0x124000
	s_waitcnt vmcnt(62) lgkmcnt(0)
	v_fmac_f32_e32 v68, v72, v6
	v_add_co_u32_e32 v72, vcc, s8, v4
	v_cvt_pk_bf16_f32 v0, v68, s0
	s_nop 0
	v_addc_co_u32_e32 v73, vcc, 0, v5, vcc
	v_fmac_f32_e32 v69, v68, v7
	v_add_co_u32_e32 v6, vcc, s79, v4
	global_store_short v[72:73], v0, off
	v_cvt_pk_bf16_f32 v0, v69, s0
	v_addc_co_u32_e32 v7, vcc, 0, v5, vcc
	global_store_short v[6:7], v0, off
	ds_read2st64_b32 v[6:7], v11 offset0:74 offset1:75
	s_mov_b32 s8, 0x12c000
	v_add_co_u32_e32 v68, vcc, s8, v4
	s_mov_b32 s8, 0x134000
	s_waitcnt vmcnt(62) lgkmcnt(0)
	v_fmac_f32_e32 v62, v69, v6
	v_addc_co_u32_e32 v69, vcc, 0, v5, vcc
	v_cvt_pk_bf16_f32 v0, v62, s0
	v_fmac_f32_e32 v63, v62, v7
	v_add_co_u32_e32 v6, vcc, s81, v4
	global_store_short v[68:69], v0, off
	v_cvt_pk_bf16_f32 v0, v63, s0
	v_addc_co_u32_e32 v7, vcc, 0, v5, vcc
	global_store_short v[6:7], v0, off
	ds_read2st64_b32 v[6:7], v11 offset0:76 offset1:77
	v_add_co_u32_e32 v62, vcc, s8, v4
	s_mov_b32 s8, 0x13c000
	s_waitcnt vmcnt(62) lgkmcnt(0)
	v_fmac_f32_e32 v59, v63, v6
	v_addc_co_u32_e32 v63, vcc, 0, v5, vcc
	v_cvt_pk_bf16_f32 v0, v59, s0
	v_fmac_f32_e32 v70, v59, v7
	v_add_co_u32_e32 v6, vcc, s83, v4
	global_store_short v[62:63], v0, off
	v_cvt_pk_bf16_f32 v0, v70, s0
	v_addc_co_u32_e32 v7, vcc, 0, v5, vcc
	global_store_short v[6:7], v0, off
	ds_read2st64_b32 v[6:7], v11 offset0:78 offset1:79
	v_add_co_u32_e32 v62, vcc, s8, v4
	s_mov_b32 s8, 0x144000
	s_nop 0
	v_addc_co_u32_e32 v63, vcc, 0, v5, vcc
	s_waitcnt vmcnt(62) lgkmcnt(0)
	v_fmac_f32_e32 v66, v70, v6
	v_cvt_pk_bf16_f32 v0, v66, s0
	v_fmac_f32_e32 v67, v66, v7
	v_add_co_u32_e32 v6, vcc, s84, v4
	global_store_short v[62:63], v0, off
	v_cvt_pk_bf16_f32 v0, v67, s0
	v_addc_co_u32_e32 v7, vcc, 0, v5, vcc
	global_store_short v[6:7], v0, off
	ds_read2st64_b32 v[6:7], v11 offset0:80 offset1:81
	v_add_co_u32_e32 v62, vcc, s8, v4
	s_mov_b32 s8, 0x14c000
	s_nop 0
	v_addc_co_u32_e32 v63, vcc, 0, v5, vcc
	s_waitcnt vmcnt(62) lgkmcnt(0)
	v_fmac_f32_e32 v64, v67, v6
	v_cvt_pk_bf16_f32 v0, v64, s0
	v_fmac_f32_e32 v65, v64, v7
	v_add_co_u32_e32 v6, vcc, s85, v4
	global_store_short v[62:63], v0, off
	v_cvt_pk_bf16_f32 v0, v65, s0
	v_addc_co_u32_e32 v7, vcc, 0, v5, vcc
	global_store_short v[6:7], v0, off
	ds_read2st64_b32 v[6:7], v11 offset0:82 offset1:83
	v_add_co_u32_e32 v62, vcc, s8, v4
	s_mov_b32 s8, 0x154000
	s_nop 0
	v_addc_co_u32_e32 v63, vcc, 0, v5, vcc
	s_waitcnt vmcnt(62) lgkmcnt(0)
	v_fmac_f32_e32 v60, v65, v6
	v_cvt_pk_bf16_f32 v0, v60, s0
	v_fmac_f32_e32 v61, v60, v7
	v_add_co_u32_e32 v6, vcc, s87, v4
	global_store_short v[62:63], v0, off
	v_cvt_pk_bf16_f32 v0, v61, s0
	v_addc_co_u32_e32 v7, vcc, 0, v5, vcc
	global_store_short v[6:7], v0, off
	ds_read2st64_b32 v[6:7], v11 offset0:84 offset1:85
	v_add_co_u32_e32 v60, vcc, s8, v4
	s_mov_b32 s8, 0x15c000
	s_waitcnt vmcnt(62) lgkmcnt(0)
	v_fmac_f32_e32 v57, v61, v6
	v_addc_co_u32_e32 v61, vcc, 0, v5, vcc
	v_cvt_pk_bf16_f32 v0, v57, s0
	v_fmac_f32_e32 v58, v57, v7
	v_add_co_u32_e32 v6, vcc, s88, v4
	global_store_short v[60:61], v0, off
	v_cvt_pk_bf16_f32 v0, v58, s0
	v_addc_co_u32_e32 v7, vcc, 0, v5, vcc
	global_store_short v[6:7], v0, off
	ds_read2st64_b32 v[6:7], v11 offset0:86 offset1:87
	s_waitcnt vmcnt(62) lgkmcnt(0)
	v_fmac_f32_e32 v55, v58, v6
	v_add_co_u32_e32 v58, vcc, s8, v4
	v_cvt_pk_bf16_f32 v0, v55, s0
	s_nop 0
	v_addc_co_u32_e32 v59, vcc, 0, v5, vcc
	v_fmac_f32_e32 v56, v55, v7
	v_add_co_u32_e32 v6, vcc, s89, v4
	global_store_short v[58:59], v0, off
	v_cvt_pk_bf16_f32 v0, v56, s0
	v_addc_co_u32_e32 v7, vcc, 0, v5, vcc
	global_store_short v[6:7], v0, off
	ds_read2st64_b32 v[6:7], v11 offset0:88 offset1:89
	s_mov_b32 s8, 0x164000
	s_waitcnt vmcnt(62) lgkmcnt(0)
; DI bf16_t f2bf(float f) { return (bf16_t)(pk2(f, 0.f) & 0xffffu); }
; DI void gla_scan(const Params& p, int G, LAS unsigned char* lds) {
;     ...
; #pragma unroll
;             for (int j2 = 0; j2 < 64; ++j2) { sp[(size_t)(n0 + j2) * 8192] = f2bf(st); st = dl[(n0 + j2) * 64 + k] * st + dv[j2]; } }
	v_fmac_f32_e32 v53, v56, v6
	v_add_co_u32_e32 v56, vcc, s8, v4
	v_cvt_pk_bf16_f32 v0, v53, s0
	s_nop 0
	v_addc_co_u32_e32 v57, vcc, 0, v5, vcc
	v_fmac_f32_e32 v54, v53, v7
	v_add_co_u32_e32 v6, vcc, s35, v4
	global_store_short v[56:57], v0, off
	v_cvt_pk_bf16_f32 v0, v54, s0
	v_addc_co_u32_e32 v7, vcc, 0, v5, vcc
	global_store_short v[6:7], v0, off
	ds_read2st64_b32 v[6:7], v11 offset0:90 offset1:91
	s_mov_b32 s8, 0x16c000
	s_waitcnt vmcnt(62) lgkmcnt(0)
	v_fmac_f32_e32 v51, v54, v6
	v_add_co_u32_e32 v54, vcc, s8, v4
	v_cvt_pk_bf16_f32 v0, v51, s0
	s_nop 0
	v_addc_co_u32_e32 v55, vcc, 0, v5, vcc
	v_fmac_f32_e32 v52, v51, v7
	v_add_co_u32_e32 v6, vcc, s86, v4
	global_store_short v[54:55], v0, off
	v_cvt_pk_bf16_f32 v0, v52, s0
	v_addc_co_u32_e32 v7, vcc, 0, v5, vcc
	global_store_short v[6:7], v0, off
	ds_read2st64_b32 v[6:7], v11 offset0:92 offset1:93
	s_mov_b32 s8, 0x174000
	s_waitcnt vmcnt(62) lgkmcnt(0)
	v_fmac_f32_e32 v49, v52, v6
	v_add_co_u32_e32 v52, vcc, s8, v4
	v_cvt_pk_bf16_f32 v0, v49, s0
	s_nop 0
	v_addc_co_u32_e32 v53, vcc, 0, v5, vcc
	v_fmac_f32_e32 v50, v49, v7
	v_add_co_u32_e32 v6, vcc, s90, v4
	global_store_short v[52:53], v0, off
	v_cvt_pk_bf16_f32 v0, v50, s0
	v_addc_co_u32_e32 v7, vcc, 0, v5, vcc
	global_store_short v[6:7], v0, off
	ds_read2st64_b32 v[6:7], v11 offset0:94 offset1:95
	s_mov_b32 s8, 0x17c000
	s_waitcnt vmcnt(62) lgkmcnt(0)
	v_fmac_f32_e32 v47, v50, v6
	v_add_co_u32_e32 v50, vcc, s8, v4
	v_cvt_pk_bf16_f32 v0, v47, s0
	s_nop 0
	v_addc_co_u32_e32 v51, vcc, 0, v5, vcc
	v_fmac_f32_e32 v48, v47, v7
	v_add_co_u32_e32 v6, vcc, s91, v4
	global_store_short v[50:51], v0, off
	v_cvt_pk_bf16_f32 v0, v48, s0
	v_addc_co_u32_e32 v7, vcc, 0, v5, vcc
	global_store_short v[6:7], v0, off
	ds_read2st64_b32 v[6:7], v11 offset0:96 offset1:97
	s_mov_b32 s8, 0x184000
	s_waitcnt vmcnt(62) lgkmcnt(0)
	v_fmac_f32_e32 v45, v48, v6
	v_add_co_u32_e32 v48, vcc, s8, v4
	v_cvt_pk_bf16_f32 v0, v45, s0
	s_nop 0
	v_addc_co_u32_e32 v49, vcc, 0, v5, vcc
	v_fmac_f32_e32 v46, v45, v7
	v_add_co_u32_e32 v6, vcc, s18, v4
	global_store_short v[48:49], v0, off
	v_cvt_pk_bf16_f32 v0, v46, s0
	v_addc_co_u32_e32 v7, vcc, 0, v5, vcc
	global_store_short v[6:7], v0, off
	ds_read2st64_b32 v[6:7], v11 offset0:98 offset1:99
	s_mov_b32 s8, 0x18c000
	s_waitcnt vmcnt(62) lgkmcnt(0)
	v_fmac_f32_e32 v43, v46, v6
	v_add_co_u32_e32 v46, vcc, s8, v4
	v_cvt_pk_bf16_f32 v0, v43, s0
	s_nop 0
	v_addc_co_u32_e32 v47, vcc, 0, v5, vcc
	v_fmac_f32_e32 v44, v43, v7
	v_add_co_u32_e32 v6, vcc, s19, v4
	global_store_short v[46:47], v0, off
	v_cvt_pk_bf16_f32 v0, v44, s0
	v_addc_co_u32_e32 v7, vcc, 0, v5, vcc
	global_store_short v[6:7], v0, off
	ds_read2st64_b32 v[6:7], v11 offset0:100 offset1:101
	s_mov_b32 s8, 0x194000
	s_waitcnt vmcnt(62) lgkmcnt(0)
	v_fmac_f32_e32 v41, v44, v6
	v_add_co_u32_e32 v44, vcc, s8, v4
	v_cvt_pk_bf16_f32 v0, v41, s0
	s_nop 0
	v_addc_co_u32_e32 v45, vcc, 0, v5, vcc
	v_fmac_f32_e32 v42, v41, v7
	v_add_co_u32_e32 v6, vcc, s36, v4
	global_store_short v[44:45], v0, off
	v_cvt_pk_bf16_f32 v0, v42, s0
	v_addc_co_u32_e32 v7, vcc, 0, v5, vcc
	global_store_short v[6:7], v0, off
	ds_read2st64_b32 v[6:7], v11 offset0:102 offset1:103
	s_mov_b32 s8, 0x19c000
	s_waitcnt vmcnt(62) lgkmcnt(0)
	v_fmac_f32_e32 v39, v42, v6
	v_add_co_u32_e32 v42, vcc, s8, v4
	v_cvt_pk_bf16_f32 v0, v39, s0
	s_nop 0
	v_addc_co_u32_e32 v43, vcc, 0, v5, vcc
	v_fmac_f32_e32 v40, v39, v7
	v_add_co_u32_e32 v6, vcc, s37, v4
	global_store_short v[42:43], v0, off
	v_cvt_pk_bf16_f32 v0, v40, s0
	v_addc_co_u32_e32 v7, vcc, 0, v5, vcc
	global_store_short v[6:7], v0, off
	ds_read2st64_b32 v[6:7], v11 offset0:104 offset1:105
	s_mov_b32 s8, 0x1a4000
	s_waitcnt vmcnt(62) lgkmcnt(0)
	v_fmac_f32_e32 v37, v40, v6
	v_add_co_u32_e32 v40, vcc, s8, v4
	v_cvt_pk_bf16_f32 v0, v37, s0
	s_nop 0
	v_addc_co_u32_e32 v41, vcc, 0, v5, vcc
	v_fmac_f32_e32 v38, v37, v7
	v_add_co_u32_e32 v6, vcc, s6, v4
	global_store_short v[40:41], v0, off
	v_cvt_pk_bf16_f32 v0, v38, s0
	v_addc_co_u32_e32 v7, vcc, 0, v5, vcc
	global_store_short v[6:7], v0, off
	ds_read2st64_b32 v[6:7], v11 offset0:106 offset1:107
	s_mov_b32 s8, 0x1ac000
	s_waitcnt vmcnt(62) lgkmcnt(0)
	v_fmac_f32_e32 v35, v38, v6
	v_add_co_u32_e32 v38, vcc, s8, v4
	v_cvt_pk_bf16_f32 v0, v35, s0
	s_nop 0
	v_addc_co_u32_e32 v39, vcc, 0, v5, vcc
	v_fmac_f32_e32 v36, v35, v7
	v_add_co_u32_e32 v6, vcc, s7, v4
	global_store_short v[38:39], v0, off
	v_cvt_pk_bf16_f32 v0, v36, s0
	v_addc_co_u32_e32 v7, vcc, 0, v5, vcc
	global_store_short v[6:7], v0, off
	ds_read2st64_b32 v[6:7], v11 offset0:108 offset1:109
	s_mov_b32 s8, 0x1b4000
	s_waitcnt vmcnt(62) lgkmcnt(0)
; DI bf16_t f2bf(float f) { return (bf16_t)(pk2(f, 0.f) & 0xffffu); }
; DI void gla_scan(const Params& p, int G, LAS unsigned char* lds) {
;     ...
;     for (int e0 = blockIdx.x * 512; e0 < 16 * 8192; e0 += G * 512) {
;         const int e = e0 + tid, bh = e0 >> 13, vk = e & 8191, k = e & 63, b = bh >> 2, h = bh & 3;
;     ...
;         for (int n0 = 0; n0 < 128; n0 += 64) { float dv[64];
; #pragma unroll
;             for (int j2 = 0; j2 < 64; ++j2) dv[j2] = __builtin_nontemporal_load(dp + (size_t)(n0 + j2) * 8192);
; #pragma unroll
;             for (int j2 = 0; j2 < 64; ++j2) { sp[(size_t)(n0 + j2) * 8192] = f2bf(st); st = dl[(n0 + j2) * 64 + k] * st + dv[j2]; } }
	v_fmac_f32_e32 v33, v36, v6
	v_add_co_u32_e32 v36, vcc, s8, v4
	v_cvt_pk_bf16_f32 v0, v33, s0
	s_nop 0
	v_addc_co_u32_e32 v37, vcc, 0, v5, vcc
	v_fmac_f32_e32 v34, v33, v7
	v_add_co_u32_e32 v6, vcc, s0, v4
	global_store_short v[36:37], v0, off
	v_cvt_pk_bf16_f32 v0, v34, s0
	v_addc_co_u32_e32 v7, vcc, 0, v5, vcc
	global_store_short v[6:7], v0, off
	ds_read2st64_b32 v[6:7], v11 offset0:110 offset1:111
	s_mov_b32 s8, 0x1bc000
	s_waitcnt vmcnt(62) lgkmcnt(0)
	v_fmac_f32_e32 v30, v34, v6
	v_add_co_u32_e32 v34, vcc, s8, v4
	v_cvt_pk_bf16_f32 v0, v30, s0
	s_nop 0
	v_addc_co_u32_e32 v35, vcc, 0, v5, vcc
	v_fmac_f32_e32 v31, v30, v7
	v_add_co_u32_e32 v6, vcc, s1, v4
	global_store_short v[34:35], v0, off
	v_cvt_pk_bf16_f32 v0, v31, s0
	v_addc_co_u32_e32 v7, vcc, 0, v5, vcc
	global_store_short v[6:7], v0, off
	ds_read2st64_b32 v[6:7], v11 offset0:112 offset1:113
	s_mov_b32 s8, 0x1c4000
	v_add_co_u32_e32 v30, vcc, s8, v4
	s_mov_b32 s8, 0x1cc000
	s_waitcnt vmcnt(62) lgkmcnt(0)
	v_fmac_f32_e32 v24, v31, v6
	v_addc_co_u32_e32 v31, vcc, 0, v5, vcc
	v_cvt_pk_bf16_f32 v0, v24, s0
	v_fmac_f32_e32 v26, v24, v7
	v_add_co_u32_e32 v6, vcc, s4, v4
	global_store_short v[30:31], v0, off
	v_cvt_pk_bf16_f32 v0, v26, s0
	v_addc_co_u32_e32 v7, vcc, 0, v5, vcc
	global_store_short v[6:7], v0, off
	ds_read2st64_b32 v[6:7], v11 offset0:114 offset1:115
	v_add_co_u32_e32 v30, vcc, s8, v4
	s_mov_b32 s8, 0x1d4000
	s_nop 0
	v_addc_co_u32_e32 v31, vcc, 0, v5, vcc
	s_waitcnt vmcnt(62) lgkmcnt(0)
	v_fmac_f32_e32 v22, v26, v6
	v_cvt_pk_bf16_f32 v0, v22, s0
	v_fmac_f32_e32 v28, v22, v7
	v_add_co_u32_e32 v6, vcc, s5, v4
	global_store_short v[30:31], v0, off
	v_cvt_pk_bf16_f32 v0, v28, s0
	v_addc_co_u32_e32 v7, vcc, 0, v5, vcc
	global_store_short v[6:7], v0, off
	ds_read2st64_b32 v[6:7], v11 offset0:116 offset1:117
	v_add_co_u32_e32 v30, vcc, s8, v4
	s_mov_b32 s8, 0x1dc000
	s_nop 0
	v_addc_co_u32_e32 v31, vcc, 0, v5, vcc
	s_waitcnt vmcnt(62) lgkmcnt(0)
	v_fmac_f32_e32 v29, v28, v6
	v_cvt_pk_bf16_f32 v0, v29, s0
	v_fmac_f32_e32 v32, v29, v7
	v_add_co_u32_e32 v6, vcc, s92, v4
	global_store_short v[30:31], v0, off
	v_cvt_pk_bf16_f32 v0, v32, s0
	v_addc_co_u32_e32 v7, vcc, 0, v5, vcc
	global_store_short v[6:7], v0, off
	ds_read2st64_b32 v[6:7], v11 offset0:118 offset1:119
	v_add_co_u32_e32 v28, vcc, s8, v4
	s_mov_b32 s8, 0x1e4000
	s_nop 0
	v_addc_co_u32_e32 v29, vcc, 0, v5, vcc
	s_waitcnt vmcnt(62) lgkmcnt(0)
	v_fmac_f32_e32 v25, v32, v6
	v_cvt_pk_bf16_f32 v0, v25, s0
	v_fmac_f32_e32 v27, v25, v7
	v_add_co_u32_e32 v6, vcc, s93, v4
	global_store_short v[28:29], v0, off
	v_cvt_pk_bf16_f32 v0, v27, s0
	v_addc_co_u32_e32 v7, vcc, 0, v5, vcc
	global_store_short v[6:7], v0, off
	ds_read2st64_b32 v[6:7], v11 offset0:120 offset1:121
	v_add_co_u32_e32 v24, vcc, s8, v4
	s_mov_b32 s8, 0x1ec000
	s_nop 0
	v_addc_co_u32_e32 v25, vcc, 0, v5, vcc
	s_waitcnt vmcnt(62) lgkmcnt(0)
	v_fmac_f32_e32 v20, v27, v6
	v_cvt_pk_bf16_f32 v0, v20, s0
	v_fmac_f32_e32 v21, v20, v7
	v_add_co_u32_e32 v6, vcc, s12, v4
	global_store_short v[24:25], v0, off
	v_cvt_pk_bf16_f32 v0, v21, s0
	v_addc_co_u32_e32 v7, vcc, 0, v5, vcc
	global_store_short v[6:7], v0, off
	ds_read2st64_b32 v[6:7], v11 offset0:122 offset1:123
	v_add_co_u32_e32 v20, vcc, s8, v4
	s_waitcnt vmcnt(62) lgkmcnt(0)
	v_fmac_f32_e32 v18, v21, v6
	v_addc_co_u32_e32 v21, vcc, 0, v5, vcc
	v_cvt_pk_bf16_f32 v0, v18, s0
	v_fmac_f32_e32 v17, v18, v7
	v_add_co_u32_e32 v6, vcc, s13, v4
	global_store_short v[20:21], v0, off
	v_cvt_pk_bf16_f32 v0, v17, s0
	v_addc_co_u32_e32 v7, vcc, 0, v5, vcc
	global_store_short v[6:7], v0, off
	ds_read2st64_b32 v[6:7], v11 offset0:124 offset1:125
	v_add_co_u32_e32 v18, vcc, 0x1f4000, v4
	s_waitcnt vmcnt(62) lgkmcnt(0)
	v_fmac_f32_e32 v9, v17, v6
	v_addc_co_u32_e32 v19, vcc, 0, v5, vcc
	v_cvt_pk_bf16_f32 v0, v9, s0
	s_waitcnt vmcnt(61)
	v_fmac_f32_e32 v8, v9, v7
	v_add_co_u32_e32 v6, vcc, 0x1f8000, v4
	global_store_short v[18:19], v0, off
	v_cvt_pk_bf16_f32 v0, v8, s0
	v_addc_co_u32_e32 v7, vcc, 0, v5, vcc
	global_store_short v[6:7], v0, off
	ds_read_b32 v0, v11 offset:32256
	v_add_co_u32_e32 v4, vcc, 0x1fc000, v4
	s_waitcnt lgkmcnt(0)
	v_fmac_f32_e32 v23, v8, v0
	v_cvt_pk_bf16_f32 v0, v23, s0
	v_addc_co_u32_e32 v5, vcc, 0, v5, vcc
	global_store_short v[4:5], v0, off
	s_cbranch_scc1 .LBB0_434
	v_readlane_b32 s90, v253, 46
	v_readlane_b32 s91, v253, 47
	v_readlane_b32 s92, v254, 23
	v_readlane_b32 s86, v253, 48
	v_readlane_b32 s93, v254, 24
